# grid barrier: waiting blocks poll the global generation word directly (no per-XCD relay hop); leader relay add removed
# speedup vs baseline: 1.0170x; 1.0077x over previous
; DI unsigned xb_ld(unsigned* p)              { return __hip_atomic_load(p, __ATOMIC_RELAXED, __HIP_MEMORY_SCOPE_AGENT); }
; DI unsigned xb_add(unsigned* p, unsigned v) { return __hip_atomic_fetch_add(p, v, __ATOMIC_RELAXED, __HIP_MEMORY_SCOPE_AGENT); }
; #define XB_SPIN(cond, bar) do { unsigned _sp = 0; while (cond) { __builtin_amdgcn_s_sleep(1); \
;     if ((++_sp & 255u) == 0u) { if (xb_ld(&(bar)[XB_TMO])) break; if (_sp > XB_SPIN_CAP) { atomicAdd(&(bar)[XB_TMO], 1u); break; } } } } while (0)
; DI void xcd_barrier(const XcdBarrier& b) {
;     ...
;     const unsigned old = xb_add(&bar[XB_XSUB(b.x)], 1u);
;     const unsigned gen = old / nloc;
;     if (old + 1u == (gen + 1u) * nloc) {
;       __builtin_amdgcn_fence(__ATOMIC_RELEASE, "agent");
;       asm volatile("s_waitcnt vmcnt(0)" ::: "memory");
;       const unsigned og = xb_add(&bar[XB_TOP], 1u);
;       const unsigned tg = og / nx;
;       if (og + 1u == (tg + 1u) * nx) xb_add(&bar[XB_TOPGEN], 1u);
;       else XB_SPIN(xb_ld(&bar[XB_TOPGEN]) == tg, bar);
;       __builtin_amdgcn_fence(__ATOMIC_ACQUIRE, "agent");
;       xb_add(&bar[XB_XGEN(b.x)], 1u);
;       asm volatile("s_waitcnt vmcnt(0)" ::: "memory");
;     } else {
;       XB_SPIN(xb_ld(&bar[XB_XGEN(b.x)]) == gen, bar);
.LBB0_65:
	s_or_b64 exec, exec, s[12:13]
	v_cvt_f32_u32_e32 v4, v2
	s_waitcnt vmcnt(0)
	v_readfirstlane_b32 s0, v3
	v_sub_u32_e32 v3, 0, v2
	v_rcp_iflag_f32_e32 v4, v4
	v_add_u32_e32 v5, s0, v1
	v_mul_f32_e32 v4, 0x4f7ffffe, v4
	v_cvt_u32_f32_e32 v4, v4
	v_mul_lo_u32 v1, v3, v4
	v_mul_hi_u32 v1, v4, v1
	v_add_u32_e32 v1, v4, v1
	v_mul_hi_u32 v1, v5, v1
	v_mul_lo_u32 v3, v1, v2
	v_sub_u32_e32 v3, v5, v3
	v_add_u32_e32 v4, 1, v1
	v_cmp_ge_u32_e32 vcc, v3, v2
	s_nop 1
	v_cndmask_b32_e32 v1, v1, v4, vcc
	v_sub_u32_e32 v4, v3, v2
	v_cndmask_b32_e32 v3, v3, v4, vcc
	v_add_u32_e32 v4, 1, v1
	v_cmp_ge_u32_e32 vcc, v3, v2
	v_add_u32_e32 v3, 1, v5
	s_nop 0
	v_cndmask_b32_e32 v1, v1, v4, vcc
	v_mul_lo_u32 v4, v2, v1
	v_add_u32_e32 v2, v4, v2
	v_cmp_ne_u32_e32 vcc, v3, v2
	s_and_saveexec_b64 s[0:1], vcc
	s_xor_b64 s[10:11], exec, s[0:1]
	s_cbranch_execz .LBB0_79
	s_waitcnt lgkmcnt(0)
	s_add_u32 s16, s22, 0x1c103500
	s_addc_u32 s17, s23, 0
	v_mov_b32_e32 v0, 0
	global_load_dword v0, v0, s[16:17] sc1
	s_waitcnt vmcnt(0)
	v_cmp_eq_u32_e32 vcc, v0, v1
	s_and_saveexec_b64 s[12:13], vcc
	s_cbranch_execz .LBB0_78
	s_add_u32 s14, s22, 0x1c100200
	s_addc_u32 s15, s23, 0
	s_mov_b32 s0, 1
	s_mov_b64 s[18:19], 0
	v_mov_b32_e32 v0, 0
	s_branch .LBB0_69

; DI unsigned xb_add(unsigned* p, unsigned v) { return __hip_atomic_fetch_add(p, v, __ATOMIC_RELAXED, __HIP_MEMORY_SCOPE_AGENT); }
; DI void xcd_barrier(const XcdBarrier& b) {
;     ...
;       __builtin_amdgcn_fence(__ATOMIC_ACQUIRE, "agent");
;       xb_add(&bar[XB_XGEN(b.x)], 1u);
;       asm volatile("s_waitcnt vmcnt(0)" ::: "memory");
.LBB0_96:
	s_or_b64 exec, exec, s[10:11]
	s_mov_b64 s[10:11], exec
	v_mbcnt_lo_u32_b32 v0, s10, 0
	v_mbcnt_hi_u32_b32 v0, s11, v0
	v_cmp_eq_u32_e32 vcc, 0, v0
	s_waitcnt vmcnt(0)
	buffer_inv sc1
	s_and_saveexec_b64 s[12:13], vcc
	s_cbranch_execz .LBB0_98
	s_bcnt1_i32_b64 s0, s[10:11]
	v_mov_b32_e32 v0, 0x2000
	v_mov_b32_e32 v1, s0
.LBB0_98:
	s_or_b64 exec, exec, s[12:13]
	s_waitcnt vmcnt(0)

; DI unsigned xb_add(unsigned* p, unsigned v) { return __hip_atomic_fetch_add(p, v, __ATOMIC_RELAXED, __HIP_MEMORY_SCOPE_AGENT); }
; DI void xcd_barrier(const XcdBarrier& b) {
;     ...
;       __builtin_amdgcn_fence(__ATOMIC_ACQUIRE, "agent");
;       xb_add(&bar[XB_XGEN(b.x)], 1u);
;       asm volatile("s_waitcnt vmcnt(0)" ::: "memory");
.LBB0_317:
	s_or_b64 exec, exec, s[10:11]
	s_mov_b64 s[10:11], exec
	v_mbcnt_lo_u32_b32 v0, s10, 0
	v_mbcnt_hi_u32_b32 v0, s11, v0
	v_cmp_eq_u32_e32 vcc, 0, v0
	s_waitcnt vmcnt(0)
	buffer_inv sc1
	s_and_saveexec_b64 s[12:13], vcc
	s_cbranch_execz .LBB0_319
	s_bcnt1_i32_b64 s0, s[10:11]
	v_mov_b32_e32 v0, 0x2000
	v_mov_b32_e32 v1, s0
.LBB0_319:
	s_or_b64 exec, exec, s[12:13]
	s_waitcnt vmcnt(0)

; DI unsigned xb_add(unsigned* p, unsigned v) { return __hip_atomic_fetch_add(p, v, __ATOMIC_RELAXED, __HIP_MEMORY_SCOPE_AGENT); }
; DI void xcd_barrier(const XcdBarrier& b) {
;     ...
;       __builtin_amdgcn_fence(__ATOMIC_ACQUIRE, "agent");
;       xb_add(&bar[XB_XGEN(b.x)], 1u);
;       asm volatile("s_waitcnt vmcnt(0)" ::: "memory");
.LBB0_399:
	s_or_b64 exec, exec, s[10:11]
	s_mov_b64 s[10:11], exec
	v_mbcnt_lo_u32_b32 v0, s10, 0
	v_mbcnt_hi_u32_b32 v0, s11, v0
	v_cmp_eq_u32_e32 vcc, 0, v0
	s_waitcnt vmcnt(0)
	buffer_inv sc1
	s_and_saveexec_b64 s[12:13], vcc
	s_cbranch_execz .LBB0_401
	s_bcnt1_i32_b64 s0, s[10:11]
	v_mov_b32_e32 v0, 0x2000
	v_mov_b32_e32 v1, s0
.LBB0_401:
	s_or_b64 exec, exec, s[12:13]
	s_waitcnt vmcnt(0)

; DI unsigned xb_ld(unsigned* p)              { return __hip_atomic_load(p, __ATOMIC_RELAXED, __HIP_MEMORY_SCOPE_AGENT); }
; DI unsigned xb_add(unsigned* p, unsigned v) { return __hip_atomic_fetch_add(p, v, __ATOMIC_RELAXED, __HIP_MEMORY_SCOPE_AGENT); }
; #define XB_SPIN(cond, bar) do { unsigned _sp = 0; while (cond) { __builtin_amdgcn_s_sleep(1); \
;     if ((++_sp & 255u) == 0u) { if (xb_ld(&(bar)[XB_TMO])) break; if (_sp > XB_SPIN_CAP) { atomicAdd(&(bar)[XB_TMO], 1u); break; } } } } while (0)
; DI void xcd_barrier(const XcdBarrier& b) {
;     ...
;     const unsigned old = xb_add(&bar[XB_XSUB(b.x)], 1u);
;     const unsigned gen = old / nloc;
;     if (old + 1u == (gen + 1u) * nloc) {
;       __builtin_amdgcn_fence(__ATOMIC_RELEASE, "agent");
;       asm volatile("s_waitcnt vmcnt(0)" ::: "memory");
;       const unsigned og = xb_add(&bar[XB_TOP], 1u);
;       const unsigned tg = og / nx;
;       if (og + 1u == (tg + 1u) * nx) xb_add(&bar[XB_TOPGEN], 1u);
;       else XB_SPIN(xb_ld(&bar[XB_TOPGEN]) == tg, bar);
;       __builtin_amdgcn_fence(__ATOMIC_ACQUIRE, "agent");
;       xb_add(&bar[XB_XGEN(b.x)], 1u);
;       asm volatile("s_waitcnt vmcnt(0)" ::: "memory");
;     } else {
;       XB_SPIN(xb_ld(&bar[XB_XGEN(b.x)]) == gen, bar);
.LBB0_442:
	s_or_b64 exec, exec, s[30:31]
	v_cvt_f32_u32_e32 v4, v2
	s_waitcnt vmcnt(0)
	v_readfirstlane_b32 s4, v3
	v_sub_u32_e32 v3, 0, v2
	v_rcp_iflag_f32_e32 v4, v4
	v_add_u32_e32 v5, s4, v1
	v_mul_f32_e32 v4, 0x4f7ffffe, v4
	v_cvt_u32_f32_e32 v4, v4
	v_mul_lo_u32 v1, v3, v4
	v_mul_hi_u32 v1, v4, v1
	v_add_u32_e32 v1, v4, v1
	v_mul_hi_u32 v1, v5, v1
	v_mul_lo_u32 v3, v1, v2
	v_sub_u32_e32 v3, v5, v3
	v_add_u32_e32 v4, 1, v1
	v_cmp_ge_u32_e32 vcc, v3, v2
	s_nop 1
	v_cndmask_b32_e32 v1, v1, v4, vcc
	v_sub_u32_e32 v4, v3, v2
	v_cndmask_b32_e32 v3, v3, v4, vcc
	v_add_u32_e32 v4, 1, v1
	v_cmp_ge_u32_e32 vcc, v3, v2
	v_add_u32_e32 v3, 1, v5
	s_nop 0
	v_cndmask_b32_e32 v1, v1, v4, vcc
	v_mul_lo_u32 v4, v2, v1
	v_add_u32_e32 v2, v4, v2
	v_cmp_ne_u32_e32 vcc, v3, v2
	s_and_saveexec_b64 s[4:5], vcc
	s_xor_b64 s[28:29], exec, s[4:5]
	s_cbranch_execz .LBB0_456
	s_waitcnt lgkmcnt(0)
	s_add_u32 s40, s22, 0x1c103500
	s_addc_u32 s41, s23, 0
	v_mov_b32_e32 v0, 0
	global_load_dword v0, v0, s[40:41] sc1
	s_waitcnt vmcnt(0)
	v_cmp_eq_u32_e32 vcc, v0, v1
	s_and_saveexec_b64 s[30:31], vcc
	s_cbranch_execz .LBB0_455
	s_add_u32 s34, s22, 0x1c100200
	s_addc_u32 s35, s23, 0
	s_mov_b32 s4, 1
	s_mov_b64 s[42:43], 0
	v_mov_b32_e32 v0, 0
	s_branch .LBB0_446

; DI unsigned xb_add(unsigned* p, unsigned v) { return __hip_atomic_fetch_add(p, v, __ATOMIC_RELAXED, __HIP_MEMORY_SCOPE_AGENT); }
; DI void xcd_barrier(const XcdBarrier& b) {
;     ...
;       __builtin_amdgcn_fence(__ATOMIC_ACQUIRE, "agent");
;       xb_add(&bar[XB_XGEN(b.x)], 1u);
;       asm volatile("s_waitcnt vmcnt(0)" ::: "memory");
.LBB0_473:
	s_or_b64 exec, exec, s[28:29]
	s_mov_b64 s[28:29], exec
	v_mbcnt_lo_u32_b32 v0, s28, 0
	v_mbcnt_hi_u32_b32 v0, s29, v0
	v_cmp_eq_u32_e32 vcc, 0, v0
	s_waitcnt vmcnt(0)
	buffer_inv sc1
	s_and_saveexec_b64 s[30:31], vcc
	s_cbranch_execz .LBB0_475
	s_bcnt1_i32_b64 s4, s[28:29]
	v_mov_b32_e32 v0, 0x2000
	v_mov_b32_e32 v1, s4
.LBB0_475:
	s_or_b64 exec, exec, s[30:31]
	s_waitcnt vmcnt(0)

; DI unsigned xb_add(unsigned* p, unsigned v) { return __hip_atomic_fetch_add(p, v, __ATOMIC_RELAXED, __HIP_MEMORY_SCOPE_AGENT); }
; DI void xcd_barrier(const XcdBarrier& b) {
;     ...
;       __builtin_amdgcn_fence(__ATOMIC_ACQUIRE, "agent");
;       xb_add(&bar[XB_XGEN(b.x)], 1u);
;       asm volatile("s_waitcnt vmcnt(0)" ::: "memory");
.LBB0_534:
	s_or_b64 exec, exec, s[28:29]
	s_mov_b64 s[28:29], exec
	v_mbcnt_lo_u32_b32 v0, s28, 0
	v_mbcnt_hi_u32_b32 v0, s29, v0
	v_cmp_eq_u32_e32 vcc, 0, v0
	s_waitcnt vmcnt(0)
	buffer_inv sc1
	s_and_saveexec_b64 s[30:31], vcc
	s_cbranch_execz .LBB0_536
	s_bcnt1_i32_b64 s4, s[28:29]
	v_mov_b32_e32 v0, 0x2000
	v_mov_b32_e32 v1, s4
.LBB0_536:
	s_or_b64 exec, exec, s[30:31]
	s_waitcnt vmcnt(0)

; DI unsigned xb_ld(unsigned* p)              { return __hip_atomic_load(p, __ATOMIC_RELAXED, __HIP_MEMORY_SCOPE_AGENT); }
; DI unsigned xb_add(unsigned* p, unsigned v) { return __hip_atomic_fetch_add(p, v, __ATOMIC_RELAXED, __HIP_MEMORY_SCOPE_AGENT); }
; #define XB_SPIN(cond, bar) do { unsigned _sp = 0; while (cond) { __builtin_amdgcn_s_sleep(1); \
;     if ((++_sp & 255u) == 0u) { if (xb_ld(&(bar)[XB_TMO])) break; if (_sp > XB_SPIN_CAP) { atomicAdd(&(bar)[XB_TMO], 1u); break; } } } } while (0)
; DI void xcd_barrier(const XcdBarrier& b) {
;     ...
;     const unsigned old = xb_add(&bar[XB_XSUB(b.x)], 1u);
;     const unsigned gen = old / nloc;
;     if (old + 1u == (gen + 1u) * nloc) {
;       __builtin_amdgcn_fence(__ATOMIC_RELEASE, "agent");
;       asm volatile("s_waitcnt vmcnt(0)" ::: "memory");
;       const unsigned og = xb_add(&bar[XB_TOP], 1u);
;       const unsigned tg = og / nx;
;       if (og + 1u == (tg + 1u) * nx) xb_add(&bar[XB_TOPGEN], 1u);
;       else XB_SPIN(xb_ld(&bar[XB_TOPGEN]) == tg, bar);
;       __builtin_amdgcn_fence(__ATOMIC_ACQUIRE, "agent");
;       xb_add(&bar[XB_XGEN(b.x)], 1u);
;       asm volatile("s_waitcnt vmcnt(0)" ::: "memory");
;     } else {
;       XB_SPIN(xb_ld(&bar[XB_XGEN(b.x)]) == gen, bar);
.LBB0_558:
	s_or_b64 exec, exec, s[40:41]
	v_cvt_f32_u32_e32 v4, v2
	s_waitcnt vmcnt(0)
	v_readfirstlane_b32 s4, v3
	v_sub_u32_e32 v3, 0, v2
	v_rcp_iflag_f32_e32 v4, v4
	v_add_u32_e32 v5, s4, v1
	v_mul_f32_e32 v4, 0x4f7ffffe, v4
	v_cvt_u32_f32_e32 v4, v4
	v_mul_lo_u32 v1, v3, v4
	v_mul_hi_u32 v1, v4, v1
	v_add_u32_e32 v1, v4, v1
	v_mul_hi_u32 v1, v5, v1
	v_mul_lo_u32 v3, v1, v2
	v_sub_u32_e32 v3, v5, v3
	v_add_u32_e32 v4, 1, v1
	v_cmp_ge_u32_e32 vcc, v3, v2
	s_nop 1
	v_cndmask_b32_e32 v1, v1, v4, vcc
	v_sub_u32_e32 v4, v3, v2
	v_cndmask_b32_e32 v3, v3, v4, vcc
	v_add_u32_e32 v4, 1, v1
	v_cmp_ge_u32_e32 vcc, v3, v2
	v_add_u32_e32 v3, 1, v5
	s_nop 0
	v_cndmask_b32_e32 v1, v1, v4, vcc
	v_mul_lo_u32 v4, v2, v1
	v_add_u32_e32 v2, v4, v2
	v_cmp_ne_u32_e32 vcc, v3, v2
	s_and_saveexec_b64 s[4:5], vcc
	s_xor_b64 s[28:29], exec, s[4:5]
	s_cbranch_execz .LBB0_572
	s_waitcnt lgkmcnt(0)
	s_add_u32 s44, s22, 0x1c103500
	s_addc_u32 s45, s23, 0
	v_mov_b32_e32 v0, 0
	global_load_dword v0, v0, s[44:45] sc1
	s_waitcnt vmcnt(0)
	v_cmp_eq_u32_e32 vcc, v0, v1
	s_and_saveexec_b64 s[40:41], vcc
	s_cbranch_execz .LBB0_571
	s_add_u32 s42, s22, 0x1c100200
	s_addc_u32 s43, s23, 0
	s_mov_b32 s4, 1
	s_mov_b64 s[46:47], 0
	v_mov_b32_e32 v0, 0
	s_branch .LBB0_562

; DI unsigned xb_add(unsigned* p, unsigned v) { return __hip_atomic_fetch_add(p, v, __ATOMIC_RELAXED, __HIP_MEMORY_SCOPE_AGENT); }
; DI void xcd_barrier(const XcdBarrier& b) {
;     ...
;       __builtin_amdgcn_fence(__ATOMIC_ACQUIRE, "agent");
;       xb_add(&bar[XB_XGEN(b.x)], 1u);
;       asm volatile("s_waitcnt vmcnt(0)" ::: "memory");
.LBB0_589:
	s_or_b64 exec, exec, s[28:29]
	s_mov_b64 s[28:29], exec
	v_mbcnt_lo_u32_b32 v0, s28, 0
	v_mbcnt_hi_u32_b32 v0, s29, v0
	v_cmp_eq_u32_e32 vcc, 0, v0
	s_waitcnt vmcnt(0)
	buffer_inv sc1
	s_and_saveexec_b64 s[40:41], vcc
	s_cbranch_execz .LBB0_591
	s_bcnt1_i32_b64 s4, s[28:29]
	v_mov_b32_e32 v0, 0x2000
	v_mov_b32_e32 v1, s4
.LBB0_591:
	s_or_b64 exec, exec, s[40:41]
	s_waitcnt vmcnt(0)

; DI unsigned xb_ld(unsigned* p)              { return __hip_atomic_load(p, __ATOMIC_RELAXED, __HIP_MEMORY_SCOPE_AGENT); }
; DI unsigned xb_add(unsigned* p, unsigned v) { return __hip_atomic_fetch_add(p, v, __ATOMIC_RELAXED, __HIP_MEMORY_SCOPE_AGENT); }
; #define XB_SPIN(cond, bar) do { unsigned _sp = 0; while (cond) { __builtin_amdgcn_s_sleep(1); \
;     if ((++_sp & 255u) == 0u) { if (xb_ld(&(bar)[XB_TMO])) break; if (_sp > XB_SPIN_CAP) { atomicAdd(&(bar)[XB_TMO], 1u); break; } } } } while (0)
; DI void xcd_barrier(const XcdBarrier& b) {
;     ...
;     const unsigned old = xb_add(&bar[XB_XSUB(b.x)], 1u);
;     const unsigned gen = old / nloc;
;     if (old + 1u == (gen + 1u) * nloc) {
;       __builtin_amdgcn_fence(__ATOMIC_RELEASE, "agent");
;       asm volatile("s_waitcnt vmcnt(0)" ::: "memory");
;       const unsigned og = xb_add(&bar[XB_TOP], 1u);
;       const unsigned tg = og / nx;
;       if (og + 1u == (tg + 1u) * nx) xb_add(&bar[XB_TOPGEN], 1u);
;       else XB_SPIN(xb_ld(&bar[XB_TOPGEN]) == tg, bar);
;       __builtin_amdgcn_fence(__ATOMIC_ACQUIRE, "agent");
;       xb_add(&bar[XB_XGEN(b.x)], 1u);
;       asm volatile("s_waitcnt vmcnt(0)" ::: "memory");
;     } else {
;       XB_SPIN(xb_ld(&bar[XB_XGEN(b.x)]) == gen, bar);
.LBB0_640:
	s_or_b64 exec, exec, s[14:15]
	v_cvt_f32_u32_e32 v4, v2
	s_waitcnt vmcnt(0)
	v_readfirstlane_b32 s4, v3
	v_sub_u32_e32 v3, 0, v2
	v_rcp_iflag_f32_e32 v4, v4
	v_add_u32_e32 v5, s4, v1
	v_mul_f32_e32 v4, 0x4f7ffffe, v4
	v_cvt_u32_f32_e32 v4, v4
	v_mul_lo_u32 v1, v3, v4
	v_mul_hi_u32 v1, v4, v1
	v_add_u32_e32 v1, v4, v1
	v_mul_hi_u32 v1, v5, v1
	v_mul_lo_u32 v3, v1, v2
	v_sub_u32_e32 v3, v5, v3
	v_add_u32_e32 v4, 1, v1
	v_cmp_ge_u32_e32 vcc, v3, v2
	s_nop 1
	v_cndmask_b32_e32 v1, v1, v4, vcc
	v_sub_u32_e32 v4, v3, v2
	v_cndmask_b32_e32 v3, v3, v4, vcc
	v_add_u32_e32 v4, 1, v1
	v_cmp_ge_u32_e32 vcc, v3, v2
	v_add_u32_e32 v3, 1, v5
	s_nop 0
	v_cndmask_b32_e32 v1, v1, v4, vcc
	v_mul_lo_u32 v4, v2, v1
	v_add_u32_e32 v2, v4, v2
	v_cmp_ne_u32_e32 vcc, v3, v2
	s_and_saveexec_b64 s[4:5], vcc
	s_xor_b64 s[12:13], exec, s[4:5]
	s_cbranch_execz .LBB0_654
	s_waitcnt lgkmcnt(0)
	s_add_u32 s18, s22, 0x1c103500
	s_addc_u32 s19, s23, 0
	v_mov_b32_e32 v0, 0
	global_load_dword v0, v0, s[18:19] sc1
	s_waitcnt vmcnt(0)
	v_cmp_eq_u32_e32 vcc, v0, v1
	s_and_saveexec_b64 s[14:15], vcc
	s_cbranch_execz .LBB0_653
	s_add_u32 s16, s22, 0x1c100200
	s_addc_u32 s17, s23, 0
	s_mov_b32 s4, 1
	s_mov_b64 s[28:29], 0
	v_mov_b32_e32 v0, 0
	s_branch .LBB0_644

; DI unsigned xb_add(unsigned* p, unsigned v) { return __hip_atomic_fetch_add(p, v, __ATOMIC_RELAXED, __HIP_MEMORY_SCOPE_AGENT); }
; DI void xcd_barrier(const XcdBarrier& b) {
;     ...
;       __builtin_amdgcn_fence(__ATOMIC_ACQUIRE, "agent");
;       xb_add(&bar[XB_XGEN(b.x)], 1u);
;       asm volatile("s_waitcnt vmcnt(0)" ::: "memory");
.LBB0_671:
	s_or_b64 exec, exec, s[12:13]
	s_mov_b64 s[12:13], exec
	v_mbcnt_lo_u32_b32 v0, s12, 0
	v_mbcnt_hi_u32_b32 v0, s13, v0
	v_cmp_eq_u32_e32 vcc, 0, v0
	s_waitcnt vmcnt(0)
	buffer_inv sc1
	s_and_saveexec_b64 s[14:15], vcc
	s_cbranch_execz .LBB0_673
	s_bcnt1_i32_b64 s4, s[12:13]
	v_mov_b32_e32 v0, 0x2000
	v_mov_b32_e32 v1, s4
.LBB0_673:
	s_or_b64 exec, exec, s[14:15]
	s_waitcnt vmcnt(0)

; DI unsigned xb_add(unsigned* p, unsigned v) { return __hip_atomic_fetch_add(p, v, __ATOMIC_RELAXED, __HIP_MEMORY_SCOPE_AGENT); }
; DI void xcd_barrier(const XcdBarrier& b) {
;     ...
;       __builtin_amdgcn_fence(__ATOMIC_ACQUIRE, "agent");
;       xb_add(&bar[XB_XGEN(b.x)], 1u);
;       asm volatile("s_waitcnt vmcnt(0)" ::: "memory");
.LBB0_745:
	s_or_b64 exec, exec, s[12:13]
	s_mov_b64 s[12:13], exec
	v_mbcnt_lo_u32_b32 v0, s12, 0
	v_mbcnt_hi_u32_b32 v0, s13, v0
	v_cmp_eq_u32_e32 vcc, 0, v0
	s_waitcnt vmcnt(0)
	buffer_inv sc1
	s_and_saveexec_b64 s[14:15], vcc
	s_cbranch_execz .LBB0_747
	s_bcnt1_i32_b64 s4, s[12:13]
	v_mov_b32_e32 v0, 0x2000
	v_mov_b32_e32 v1, s4
.LBB0_747:
	s_or_b64 exec, exec, s[14:15]
	s_waitcnt vmcnt(0)

; DI unsigned xb_add(unsigned* p, unsigned v) { return __hip_atomic_fetch_add(p, v, __ATOMIC_RELAXED, __HIP_MEMORY_SCOPE_AGENT); }
; DI void xcd_barrier(const XcdBarrier& b) {
;     ...
;       __builtin_amdgcn_fence(__ATOMIC_ACQUIRE, "agent");
;       xb_add(&bar[XB_XGEN(b.x)], 1u);
;       asm volatile("s_waitcnt vmcnt(0)" ::: "memory");
.LBB0_804:
	s_or_b64 exec, exec, s[12:13]
	s_mov_b64 s[12:13], exec
	v_mbcnt_lo_u32_b32 v0, s12, 0
	v_mbcnt_hi_u32_b32 v0, s13, v0
	v_cmp_eq_u32_e32 vcc, 0, v0
	s_waitcnt vmcnt(0)
	buffer_inv sc1
	s_and_saveexec_b64 s[14:15], vcc
	s_cbranch_execz .LBB0_806
	s_bcnt1_i32_b64 s4, s[12:13]
	v_mov_b32_e32 v0, 0x2000
	v_mov_b32_e32 v1, s4
.LBB0_806:
	s_or_b64 exec, exec, s[14:15]
	s_waitcnt vmcnt(0)

; DI unsigned xb_add(unsigned* p, unsigned v) { return __hip_atomic_fetch_add(p, v, __ATOMIC_RELAXED, __HIP_MEMORY_SCOPE_AGENT); }
; DI void xcd_barrier(const XcdBarrier& b) {
;     ...
;       __builtin_amdgcn_fence(__ATOMIC_ACQUIRE, "agent");
;       xb_add(&bar[XB_XGEN(b.x)], 1u);
;       asm volatile("s_waitcnt vmcnt(0)" ::: "memory");
.LBB0_878:
	s_or_b64 exec, exec, s[12:13]
	s_mov_b64 s[12:13], exec
	v_mbcnt_lo_u32_b32 v0, s12, 0
	v_mbcnt_hi_u32_b32 v0, s13, v0
	v_cmp_eq_u32_e32 vcc, 0, v0
	s_waitcnt vmcnt(0)
	buffer_inv sc1
	s_and_saveexec_b64 s[14:15], vcc
	s_cbranch_execz .LBB0_880
	s_bcnt1_i32_b64 s4, s[12:13]
	v_mov_b32_e32 v0, 0x2000
	v_mov_b32_e32 v1, s4
.LBB0_880:
	s_or_b64 exec, exec, s[14:15]
	s_waitcnt vmcnt(0)

; DI unsigned xb_add(unsigned* p, unsigned v) { return __hip_atomic_fetch_add(p, v, __ATOMIC_RELAXED, __HIP_MEMORY_SCOPE_AGENT); }
; DI void xcd_barrier(const XcdBarrier& b) {
;     ...
;       __builtin_amdgcn_fence(__ATOMIC_ACQUIRE, "agent");
;       xb_add(&bar[XB_XGEN(b.x)], 1u);
;       asm volatile("s_waitcnt vmcnt(0)" ::: "memory");
.LBB0_933:
	s_or_b64 exec, exec, s[12:13]
	s_mov_b64 s[12:13], exec
	v_mbcnt_lo_u32_b32 v0, s12, 0
	v_mbcnt_hi_u32_b32 v0, s13, v0
	v_cmp_eq_u32_e32 vcc, 0, v0
	s_waitcnt vmcnt(0)
	buffer_inv sc1
	s_and_saveexec_b64 s[14:15], vcc
	s_cbranch_execz .LBB0_935
	s_bcnt1_i32_b64 s4, s[12:13]
	v_mov_b32_e32 v0, 0x2000
	v_mov_b32_e32 v1, s4
.LBB0_935:
	s_or_b64 exec, exec, s[14:15]
	s_waitcnt vmcnt(0)

; DI unsigned xb_add(unsigned* p, unsigned v) { return __hip_atomic_fetch_add(p, v, __ATOMIC_RELAXED, __HIP_MEMORY_SCOPE_AGENT); }
; DI void xcd_barrier(const XcdBarrier& b) {
;     ...
;       __builtin_amdgcn_fence(__ATOMIC_ACQUIRE, "agent");
;       xb_add(&bar[XB_XGEN(b.x)], 1u);
;       asm volatile("s_waitcnt vmcnt(0)" ::: "memory");
.LBB0_1049:
	s_or_b64 exec, exec, s[12:13]
	s_mov_b64 s[12:13], exec
	v_mbcnt_lo_u32_b32 v0, s12, 0
	v_mbcnt_hi_u32_b32 v0, s13, v0
	v_cmp_eq_u32_e32 vcc, 0, v0
	s_waitcnt vmcnt(0)
	buffer_inv sc1
	s_and_saveexec_b64 s[14:15], vcc
	s_cbranch_execz .LBB0_1051
	s_bcnt1_i32_b64 s4, s[12:13]
	v_mov_b32_e32 v0, 0x2000
	v_mov_b32_e32 v1, s4
.LBB0_1051:
	s_or_b64 exec, exec, s[14:15]
	s_waitcnt vmcnt(0)

; DI unsigned xb_ld(unsigned* p)              { return __hip_atomic_load(p, __ATOMIC_RELAXED, __HIP_MEMORY_SCOPE_AGENT); }
; DI unsigned xb_add(unsigned* p, unsigned v) { return __hip_atomic_fetch_add(p, v, __ATOMIC_RELAXED, __HIP_MEMORY_SCOPE_AGENT); }
; #define XB_SPIN(cond, bar) do { unsigned _sp = 0; while (cond) { __builtin_amdgcn_s_sleep(1); \
;     if ((++_sp & 255u) == 0u) { if (xb_ld(&(bar)[XB_TMO])) break; if (_sp > XB_SPIN_CAP) { atomicAdd(&(bar)[XB_TMO], 1u); break; } } } } while (0)
; DI void xcd_barrier(const XcdBarrier& b) {
;     ...
;     const unsigned old = xb_add(&bar[XB_XSUB(b.x)], 1u);
;     const unsigned gen = old / nloc;
;     if (old + 1u == (gen + 1u) * nloc) {
;       __builtin_amdgcn_fence(__ATOMIC_RELEASE, "agent");
;       asm volatile("s_waitcnt vmcnt(0)" ::: "memory");
;       const unsigned og = xb_add(&bar[XB_TOP], 1u);
;       const unsigned tg = og / nx;
;       if (og + 1u == (tg + 1u) * nx) xb_add(&bar[XB_TOPGEN], 1u);
;       else XB_SPIN(xb_ld(&bar[XB_TOPGEN]) == tg, bar);
;       __builtin_amdgcn_fence(__ATOMIC_ACQUIRE, "agent");
;       xb_add(&bar[XB_XGEN(b.x)], 1u);
;       asm volatile("s_waitcnt vmcnt(0)" ::: "memory");
;     } else {
;       XB_SPIN(xb_ld(&bar[XB_XGEN(b.x)]) == gen, bar);
.LBB0_1221:
	s_or_b64 exec, exec, s[14:15]
	v_cvt_f32_u32_e32 v4, v2
	s_waitcnt vmcnt(0)
	v_readfirstlane_b32 s0, v3
	v_sub_u32_e32 v3, 0, v2
	v_rcp_iflag_f32_e32 v4, v4
	v_add_u32_e32 v5, s0, v1
	v_mul_f32_e32 v4, 0x4f7ffffe, v4
	v_cvt_u32_f32_e32 v4, v4
	v_mul_lo_u32 v1, v3, v4
	v_mul_hi_u32 v1, v4, v1
	v_add_u32_e32 v1, v4, v1
	v_mul_hi_u32 v1, v5, v1
	v_mul_lo_u32 v3, v1, v2
	v_sub_u32_e32 v3, v5, v3
	v_add_u32_e32 v4, 1, v1
	v_cmp_ge_u32_e32 vcc, v3, v2
	s_nop 1
	v_cndmask_b32_e32 v1, v1, v4, vcc
	v_sub_u32_e32 v4, v3, v2
	v_cndmask_b32_e32 v3, v3, v4, vcc
	v_add_u32_e32 v4, 1, v1
	v_cmp_ge_u32_e32 vcc, v3, v2
	v_add_u32_e32 v3, 1, v5
	s_nop 0
	v_cndmask_b32_e32 v1, v1, v4, vcc
	v_mul_lo_u32 v4, v2, v1
	v_add_u32_e32 v2, v4, v2
	v_cmp_ne_u32_e32 vcc, v3, v2
	s_and_saveexec_b64 s[4:5], vcc
	s_xor_b64 s[12:13], exec, s[4:5]
	s_cbranch_execz .LBB0_1235
	s_waitcnt lgkmcnt(0)
	s_add_u32 s18, s22, 0x1c103500
	s_addc_u32 s19, s23, 0
	v_mov_b32_e32 v0, 0
	global_load_dword v0, v0, s[18:19] sc1
	s_waitcnt vmcnt(0)
	v_cmp_eq_u32_e32 vcc, v0, v1
	s_and_saveexec_b64 s[14:15], vcc
	s_cbranch_execz .LBB0_1234
	s_add_u32 s16, s22, 0x1c100200
	s_addc_u32 s17, s23, 0
	s_mov_b32 s4, 1
	s_mov_b64 s[20:21], 0
	v_mov_b32_e32 v0, 0
	s_branch .LBB0_1225

; DI unsigned xb_add(unsigned* p, unsigned v) { return __hip_atomic_fetch_add(p, v, __ATOMIC_RELAXED, __HIP_MEMORY_SCOPE_AGENT); }
; DI void xcd_barrier(const XcdBarrier& b) {
;     ...
;       __builtin_amdgcn_fence(__ATOMIC_ACQUIRE, "agent");
;       xb_add(&bar[XB_XGEN(b.x)], 1u);
;       asm volatile("s_waitcnt vmcnt(0)" ::: "memory");
.LBB0_1252:
	s_or_b64 exec, exec, s[12:13]
	s_mov_b64 s[12:13], exec
	v_mbcnt_lo_u32_b32 v0, s12, 0
	v_mbcnt_hi_u32_b32 v0, s13, v0
	v_cmp_eq_u32_e32 vcc, 0, v0
	s_waitcnt vmcnt(0)
	buffer_inv sc1
	s_and_saveexec_b64 s[14:15], vcc
	s_cbranch_execz .LBB0_1254
	s_bcnt1_i32_b64 s0, s[12:13]
	v_mov_b32_e32 v0, 0x2000
	v_mov_b32_e32 v1, s0
.LBB0_1254:
	s_or_b64 exec, exec, s[14:15]
	s_waitcnt vmcnt(0)

; DI unsigned xb_add(unsigned* p, unsigned v) { return __hip_atomic_fetch_add(p, v, __ATOMIC_RELAXED, __HIP_MEMORY_SCOPE_AGENT); }
; DI void xcd_barrier(const XcdBarrier& b) {
;     ...
;       __builtin_amdgcn_fence(__ATOMIC_ACQUIRE, "agent");
;       xb_add(&bar[XB_XGEN(b.x)], 1u);
;       asm volatile("s_waitcnt vmcnt(0)" ::: "memory");
.LBB0_1311:
	s_or_b64 exec, exec, s[12:13]
	s_mov_b64 s[12:13], exec
	v_mbcnt_lo_u32_b32 v0, s12, 0
	v_mbcnt_hi_u32_b32 v0, s13, v0
	v_cmp_eq_u32_e32 vcc, 0, v0
	s_waitcnt vmcnt(0)
	buffer_inv sc1
	s_and_saveexec_b64 s[14:15], vcc
	s_cbranch_execz .LBB0_1313
	s_bcnt1_i32_b64 s0, s[12:13]
	v_mov_b32_e32 v0, 0x2000
	v_mov_b32_e32 v1, s0
.LBB0_1313:
	s_or_b64 exec, exec, s[14:15]
	s_waitcnt vmcnt(0)

; DI unsigned xb_add(unsigned* p, unsigned v) { return __hip_atomic_fetch_add(p, v, __ATOMIC_RELAXED, __HIP_MEMORY_SCOPE_AGENT); }
; DI void xcd_barrier(const XcdBarrier& b) {
;     ...
;       __builtin_amdgcn_fence(__ATOMIC_ACQUIRE, "agent");
;       xb_add(&bar[XB_XGEN(b.x)], 1u);
;       asm volatile("s_waitcnt vmcnt(0)" ::: "memory");
.LBB0_1372:
	s_or_b64 exec, exec, s[12:13]
	s_mov_b64 s[12:13], exec
	v_mbcnt_lo_u32_b32 v0, s12, 0
	v_mbcnt_hi_u32_b32 v0, s13, v0
	v_cmp_eq_u32_e32 vcc, 0, v0
	s_waitcnt vmcnt(0)
	buffer_inv sc1
	s_and_saveexec_b64 s[14:15], vcc
	s_cbranch_execz .LBB0_1374
	s_bcnt1_i32_b64 s0, s[12:13]
	v_mov_b32_e32 v0, 0x2000
	v_mov_b32_e32 v1, s0
.LBB0_1374:
	s_or_b64 exec, exec, s[14:15]
	s_waitcnt vmcnt(0)

; DI unsigned xb_add(unsigned* p, unsigned v) { return __hip_atomic_fetch_add(p, v, __ATOMIC_RELAXED, __HIP_MEMORY_SCOPE_AGENT); }
; DI void xcd_barrier(const XcdBarrier& b) {
;     ...
;       __builtin_amdgcn_fence(__ATOMIC_ACQUIRE, "agent");
;       xb_add(&bar[XB_XGEN(b.x)], 1u);
;       asm volatile("s_waitcnt vmcnt(0)" ::: "memory");
.LBB0_1427:
	s_or_b64 exec, exec, s[12:13]
	s_mov_b64 s[12:13], exec
	v_mbcnt_lo_u32_b32 v0, s12, 0
	v_mbcnt_hi_u32_b32 v0, s13, v0
	v_cmp_eq_u32_e32 vcc, 0, v0
	s_waitcnt vmcnt(0)
	buffer_inv sc1
	s_and_saveexec_b64 s[14:15], vcc
	s_cbranch_execz .LBB0_1429
	s_bcnt1_i32_b64 s0, s[12:13]
	v_mov_b32_e32 v0, 0x2000
	v_mov_b32_e32 v1, s0
.LBB0_1429:
	s_or_b64 exec, exec, s[14:15]
	s_waitcnt vmcnt(0)

; DI unsigned xb_add(unsigned* p, unsigned v) { return __hip_atomic_fetch_add(p, v, __ATOMIC_RELAXED, __HIP_MEMORY_SCOPE_AGENT); }
; DI void xcd_barrier(const XcdBarrier& b) {
;     ...
;       __builtin_amdgcn_fence(__ATOMIC_ACQUIRE, "agent");
;       xb_add(&bar[XB_XGEN(b.x)], 1u);
;       asm volatile("s_waitcnt vmcnt(0)" ::: "memory");
.LBB0_1494:
	s_or_b64 exec, exec, s[10:11]
	s_mov_b64 s[10:11], exec
	v_mbcnt_lo_u32_b32 v0, s10, 0
	v_mbcnt_hi_u32_b32 v0, s11, v0
	v_cmp_eq_u32_e32 vcc, 0, v0
	s_waitcnt vmcnt(0)
	buffer_inv sc1
	s_and_saveexec_b64 s[12:13], vcc
	s_cbranch_execz .LBB0_1496
	s_bcnt1_i32_b64 s0, s[10:11]
	v_mov_b32_e32 v0, 0x2000
	v_mov_b32_e32 v1, s0
.LBB0_1496:
	s_or_b64 exec, exec, s[12:13]
	s_waitcnt vmcnt(0)

; DI unsigned xb_ld(unsigned* p)              { return __hip_atomic_load(p, __ATOMIC_RELAXED, __HIP_MEMORY_SCOPE_AGENT); }
; DI unsigned xb_add(unsigned* p, unsigned v) { return __hip_atomic_fetch_add(p, v, __ATOMIC_RELAXED, __HIP_MEMORY_SCOPE_AGENT); }
; #define XB_SPIN(cond, bar) do { unsigned _sp = 0; while (cond) { __builtin_amdgcn_s_sleep(1); \
;     if ((++_sp & 255u) == 0u) { if (xb_ld(&(bar)[XB_TMO])) break; if (_sp > XB_SPIN_CAP) { atomicAdd(&(bar)[XB_TMO], 1u); break; } } } } while (0)
; DI void xcd_barrier(const XcdBarrier& b) {
;     ...
;     const unsigned old = xb_add(&bar[XB_XSUB(b.x)], 1u);
;     const unsigned gen = old / nloc;
;     if (old + 1u == (gen + 1u) * nloc) {
;       __builtin_amdgcn_fence(__ATOMIC_RELEASE, "agent");
;       asm volatile("s_waitcnt vmcnt(0)" ::: "memory");
;       const unsigned og = xb_add(&bar[XB_TOP], 1u);
;       const unsigned tg = og / nx;
;       if (og + 1u == (tg + 1u) * nx) xb_add(&bar[XB_TOPGEN], 1u);
;       else XB_SPIN(xb_ld(&bar[XB_TOPGEN]) == tg, bar);
;       __builtin_amdgcn_fence(__ATOMIC_ACQUIRE, "agent");
;       xb_add(&bar[XB_XGEN(b.x)], 1u);
;       asm volatile("s_waitcnt vmcnt(0)" ::: "memory");
;     } else {
;       XB_SPIN(xb_ld(&bar[XB_XGEN(b.x)]) == gen, bar);
.LBB0_1537:
	s_or_b64 exec, exec, s[12:13]
	v_cvt_f32_u32_e32 v4, v2
	s_waitcnt vmcnt(0)
	v_readfirstlane_b32 s0, v3
	v_sub_u32_e32 v3, 0, v2
	v_rcp_iflag_f32_e32 v4, v4
	v_add_u32_e32 v5, s0, v1
	v_mul_f32_e32 v4, 0x4f7ffffe, v4
	v_cvt_u32_f32_e32 v4, v4
	v_mul_lo_u32 v1, v3, v4
	v_mul_hi_u32 v1, v4, v1
	v_add_u32_e32 v1, v4, v1
	v_mul_hi_u32 v1, v5, v1
	v_mul_lo_u32 v3, v1, v2
	v_sub_u32_e32 v3, v5, v3
	v_add_u32_e32 v4, 1, v1
	v_cmp_ge_u32_e32 vcc, v3, v2
	s_nop 1
	v_cndmask_b32_e32 v1, v1, v4, vcc
	v_sub_u32_e32 v4, v3, v2
	v_cndmask_b32_e32 v3, v3, v4, vcc
	v_add_u32_e32 v4, 1, v1
	v_cmp_ge_u32_e32 vcc, v3, v2
	v_add_u32_e32 v3, 1, v5
	s_nop 0
	v_cndmask_b32_e32 v1, v1, v4, vcc
	v_mul_lo_u32 v4, v2, v1
	v_add_u32_e32 v2, v4, v2
	v_cmp_ne_u32_e32 vcc, v3, v2
	s_and_saveexec_b64 s[0:1], vcc
	v_readlane_b32 s2, v255, 0
	s_xor_b64 s[10:11], exec, s[0:1]
	v_readlane_b32 s3, v255, 1
	s_cbranch_execz .LBB0_1551
	s_waitcnt lgkmcnt(0)
	s_add_u32 s16, s22, 0x1c103500
	s_addc_u32 s17, s23, 0
	v_mov_b32_e32 v0, 0
	global_load_dword v0, v0, s[16:17] sc1
	s_waitcnt vmcnt(0)
	v_cmp_eq_u32_e32 vcc, v0, v1
	s_and_saveexec_b64 s[12:13], vcc
	s_cbranch_execz .LBB0_1550
	s_add_u32 s14, s22, 0x1c100200
	s_addc_u32 s15, s23, 0
	s_mov_b32 s0, 1
	s_mov_b64 s[18:19], 0
	v_mov_b32_e32 v0, 0
	s_branch .LBB0_1541

; DI unsigned xb_add(unsigned* p, unsigned v) { return __hip_atomic_fetch_add(p, v, __ATOMIC_RELAXED, __HIP_MEMORY_SCOPE_AGENT); }
; DI void xcd_barrier(const XcdBarrier& b) {
;     ...
;       __builtin_amdgcn_fence(__ATOMIC_ACQUIRE, "agent");
;       xb_add(&bar[XB_XGEN(b.x)], 1u);
;       asm volatile("s_waitcnt vmcnt(0)" ::: "memory");
.LBB0_1568:
	s_or_b64 exec, exec, s[10:11]
	s_mov_b64 s[10:11], exec
	v_mbcnt_lo_u32_b32 v0, s10, 0
	v_mbcnt_hi_u32_b32 v0, s11, v0
	v_cmp_eq_u32_e32 vcc, 0, v0
	s_waitcnt vmcnt(0)
	buffer_inv sc1
	s_and_saveexec_b64 s[12:13], vcc
	s_cbranch_execz .LBB0_1570
	s_bcnt1_i32_b64 s0, s[10:11]
	v_mov_b32_e32 v0, 0x2000
	v_mov_b32_e32 v1, s0
.LBB0_1570:
	s_or_b64 exec, exec, s[12:13]
	s_waitcnt vmcnt(0)

; DI unsigned xb_ld(unsigned* p)              { return __hip_atomic_load(p, __ATOMIC_RELAXED, __HIP_MEMORY_SCOPE_AGENT); }
; DI unsigned xb_add(unsigned* p, unsigned v) { return __hip_atomic_fetch_add(p, v, __ATOMIC_RELAXED, __HIP_MEMORY_SCOPE_AGENT); }
; #define XB_SPIN(cond, bar) do { unsigned _sp = 0; while (cond) { __builtin_amdgcn_s_sleep(1); \
;     if ((++_sp & 255u) == 0u) { if (xb_ld(&(bar)[XB_TMO])) break; if (_sp > XB_SPIN_CAP) { atomicAdd(&(bar)[XB_TMO], 1u); break; } } } } while (0)
; DI void xcd_barrier(const XcdBarrier& b) {
;     ...
;     const unsigned old = xb_add(&bar[XB_XSUB(b.x)], 1u);
;     const unsigned gen = old / nloc;
;     if (old + 1u == (gen + 1u) * nloc) {
;       __builtin_amdgcn_fence(__ATOMIC_RELEASE, "agent");
;       asm volatile("s_waitcnt vmcnt(0)" ::: "memory");
;       const unsigned og = xb_add(&bar[XB_TOP], 1u);
;       const unsigned tg = og / nx;
;       if (og + 1u == (tg + 1u) * nx) xb_add(&bar[XB_TOPGEN], 1u);
;       else XB_SPIN(xb_ld(&bar[XB_TOPGEN]) == tg, bar);
;       __builtin_amdgcn_fence(__ATOMIC_ACQUIRE, "agent");
;       xb_add(&bar[XB_XGEN(b.x)], 1u);
;       asm volatile("s_waitcnt vmcnt(0)" ::: "memory");
;     } else {
;       XB_SPIN(xb_ld(&bar[XB_XGEN(b.x)]) == gen, bar);
.LBB0_1596:
	s_or_b64 exec, exec, s[10:11]
	v_cvt_f32_u32_e32 v4, v2
	s_waitcnt vmcnt(0)
	v_readfirstlane_b32 s0, v3
	v_sub_u32_e32 v3, 0, v2
	v_rcp_iflag_f32_e32 v4, v4
	v_add_u32_e32 v5, s0, v1
	v_mul_f32_e32 v4, 0x4f7ffffe, v4
	v_cvt_u32_f32_e32 v4, v4
	v_mul_lo_u32 v1, v3, v4
	v_mul_hi_u32 v1, v4, v1
	v_add_u32_e32 v1, v4, v1
	v_mul_hi_u32 v1, v5, v1
	v_mul_lo_u32 v3, v1, v2
	v_sub_u32_e32 v3, v5, v3
	v_add_u32_e32 v4, 1, v1
	v_cmp_ge_u32_e32 vcc, v3, v2
	s_nop 1
	v_cndmask_b32_e32 v1, v1, v4, vcc
	v_sub_u32_e32 v4, v3, v2
	v_cndmask_b32_e32 v3, v3, v4, vcc
	v_add_u32_e32 v4, 1, v1
	v_cmp_ge_u32_e32 vcc, v3, v2
	v_add_u32_e32 v3, 1, v5
	s_nop 0
	v_cndmask_b32_e32 v1, v1, v4, vcc
	v_mul_lo_u32 v4, v2, v1
	v_add_u32_e32 v2, v4, v2
	v_cmp_ne_u32_e32 vcc, v3, v2
	s_and_saveexec_b64 s[0:1], vcc
	s_xor_b64 s[8:9], exec, s[0:1]
	s_cbranch_execz .LBB0_1610
	s_waitcnt lgkmcnt(0)
	s_add_u32 s14, s22, 0x1c103500
	s_addc_u32 s15, s23, 0
	v_mov_b32_e32 v0, 0
	global_load_dword v0, v0, s[14:15] sc1
	s_waitcnt vmcnt(0)
	v_cmp_eq_u32_e32 vcc, v0, v1
	s_and_saveexec_b64 s[10:11], vcc
	s_cbranch_execz .LBB0_1609
	s_add_u32 s12, s22, 0x1c100200
	s_addc_u32 s13, s23, 0
	s_mov_b32 s0, 1
	s_mov_b64 s[16:17], 0
	v_mov_b32_e32 v0, 0
	s_branch .LBB0_1600

; DI unsigned xb_add(unsigned* p, unsigned v) { return __hip_atomic_fetch_add(p, v, __ATOMIC_RELAXED, __HIP_MEMORY_SCOPE_AGENT); }
; DI void xcd_barrier(const XcdBarrier& b) {
;     ...
;       __builtin_amdgcn_fence(__ATOMIC_ACQUIRE, "agent");
;       xb_add(&bar[XB_XGEN(b.x)], 1u);
;       asm volatile("s_waitcnt vmcnt(0)" ::: "memory");
.LBB0_1627:
	s_or_b64 exec, exec, s[8:9]
	s_mov_b64 s[8:9], exec
	v_mbcnt_lo_u32_b32 v0, s8, 0
	v_mbcnt_hi_u32_b32 v0, s9, v0
	v_cmp_eq_u32_e32 vcc, 0, v0
	s_waitcnt vmcnt(0)
	buffer_inv sc1
	s_and_saveexec_b64 s[10:11], vcc
	s_cbranch_execz .LBB0_1629
	s_bcnt1_i32_b64 s0, s[8:9]
	v_mov_b32_e32 v0, 0x2000
	v_mov_b32_e32 v1, s0
.LBB0_1629:
	s_or_b64 exec, exec, s[10:11]
	s_waitcnt vmcnt(0)

; DI unsigned xb_ld(unsigned* p)              { return __hip_atomic_load(p, __ATOMIC_RELAXED, __HIP_MEMORY_SCOPE_AGENT); }
; DI unsigned xb_add(unsigned* p, unsigned v) { return __hip_atomic_fetch_add(p, v, __ATOMIC_RELAXED, __HIP_MEMORY_SCOPE_AGENT); }
; #define XB_SPIN(cond, bar) do { unsigned _sp = 0; while (cond) { __builtin_amdgcn_s_sleep(1); \
;     if ((++_sp & 255u) == 0u) { if (xb_ld(&(bar)[XB_TMO])) break; if (_sp > XB_SPIN_CAP) { atomicAdd(&(bar)[XB_TMO], 1u); break; } } } } while (0)
; DI void xcd_barrier(const XcdBarrier& b) {
;     ...
;     const unsigned old = xb_add(&bar[XB_XSUB(b.x)], 1u);
;     const unsigned gen = old / nloc;
;     if (old + 1u == (gen + 1u) * nloc) {
;       __builtin_amdgcn_fence(__ATOMIC_RELEASE, "agent");
;       asm volatile("s_waitcnt vmcnt(0)" ::: "memory");
;       const unsigned og = xb_add(&bar[XB_TOP], 1u);
;       const unsigned tg = og / nx;
;       if (og + 1u == (tg + 1u) * nx) xb_add(&bar[XB_TOPGEN], 1u);
;       else XB_SPIN(xb_ld(&bar[XB_TOPGEN]) == tg, bar);
;       __builtin_amdgcn_fence(__ATOMIC_ACQUIRE, "agent");
;       xb_add(&bar[XB_XGEN(b.x)], 1u);
;       asm volatile("s_waitcnt vmcnt(0)" ::: "memory");
;     } else {
;       XB_SPIN(xb_ld(&bar[XB_XGEN(b.x)]) == gen, bar);
.LBB0_1670:
	s_or_b64 exec, exec, s[8:9]
	v_cvt_f32_u32_e32 v4, v2
	s_waitcnt vmcnt(0)
	v_readfirstlane_b32 s0, v3
	v_sub_u32_e32 v3, 0, v2
	v_rcp_iflag_f32_e32 v4, v4
	v_add_u32_e32 v5, s0, v1
	v_mul_f32_e32 v4, 0x4f7ffffe, v4
	v_cvt_u32_f32_e32 v4, v4
	v_mul_lo_u32 v1, v3, v4
	v_mul_hi_u32 v1, v4, v1
	v_add_u32_e32 v1, v4, v1
	v_mul_hi_u32 v1, v5, v1
	v_mul_lo_u32 v3, v1, v2
	v_sub_u32_e32 v3, v5, v3
	v_add_u32_e32 v4, 1, v1
	v_cmp_ge_u32_e32 vcc, v3, v2
	s_nop 1
	v_cndmask_b32_e32 v1, v1, v4, vcc
	v_sub_u32_e32 v4, v3, v2
	v_cndmask_b32_e32 v3, v3, v4, vcc
	v_add_u32_e32 v4, 1, v1
	v_cmp_ge_u32_e32 vcc, v3, v2
	v_add_u32_e32 v3, 1, v5
	s_nop 0
	v_cndmask_b32_e32 v1, v1, v4, vcc
	v_mul_lo_u32 v4, v2, v1
	v_add_u32_e32 v2, v4, v2
	v_cmp_ne_u32_e32 vcc, v3, v2
	s_and_saveexec_b64 s[0:1], vcc
	s_xor_b64 s[6:7], exec, s[0:1]
	s_cbranch_execz .LBB0_1684
	s_waitcnt lgkmcnt(0)
	s_add_u32 s12, s22, 0x1c103500
	s_addc_u32 s13, s23, 0
	v_mov_b32_e32 v0, 0
	global_load_dword v0, v0, s[12:13] sc1
	s_waitcnt vmcnt(0)
	v_cmp_eq_u32_e32 vcc, v0, v1
	s_and_saveexec_b64 s[8:9], vcc
	s_cbranch_execz .LBB0_1683
	s_add_u32 s10, s22, 0x1c100200
	s_addc_u32 s11, s23, 0
	s_mov_b32 s0, 1
	s_mov_b64 s[14:15], 0
	v_mov_b32_e32 v0, 0
	s_branch .LBB0_1674

; DI unsigned xb_add(unsigned* p, unsigned v) { return __hip_atomic_fetch_add(p, v, __ATOMIC_RELAXED, __HIP_MEMORY_SCOPE_AGENT); }
; DI void xcd_barrier(const XcdBarrier& b) {
;     ...
;       __builtin_amdgcn_fence(__ATOMIC_ACQUIRE, "agent");
;       xb_add(&bar[XB_XGEN(b.x)], 1u);
;       asm volatile("s_waitcnt vmcnt(0)" ::: "memory");
.LBB0_1701:
	s_or_b64 exec, exec, s[6:7]
	s_mov_b64 s[6:7], exec
	v_mbcnt_lo_u32_b32 v0, s6, 0
	v_mbcnt_hi_u32_b32 v0, s7, v0
	v_cmp_eq_u32_e32 vcc, 0, v0
	s_waitcnt vmcnt(0)
	buffer_inv sc1
	s_and_saveexec_b64 s[8:9], vcc
	s_cbranch_execz .LBB0_1703
	s_bcnt1_i32_b64 s0, s[6:7]
	v_mov_b32_e32 v0, 0x2000
	v_mov_b32_e32 v1, s0
.LBB0_1703:
	s_or_b64 exec, exec, s[8:9]
	s_waitcnt vmcnt(0)
